# mix2 unit start: the two log-decay loads and four B|C tile loads issued back to back with counted waits (was six load-wait-use round trips)
# baseline (speedup 1.0000x reference)
.LBB0_40:
	s_lshl_b32 s0, s8, 5
	s_and_b32 s9, s0, 0x60
	s_cmpk_gt_i32 s8, 0x7f
	s_mov_b64 s[4:5], -1
	s_cbranch_scc0 .LBB0_101
	s_add_i32 s0, s8, 0xffffff80
	s_lshr_b32 s4, s0, 3
	s_bfe_u32 s10, s8, 0x10002
	s_lshl_b32 s0, s4, 1
	s_or_b32 s0, s0, s10
	s_lshl_b32 s5, s4, 8
	s_lshl_b32 s11, s10, 7
	s_lshl_b64 s[6:7], s[0:1], 13
	v_readlane_b32 s12, v253, 56
	v_readlane_b32 s13, v253, 57
	s_add_u32 s0, s12, s6
	v_mov_b32_e32 v8, v171
	s_addc_u32 s7, s13, s7
	s_lshl_b32 s6, s9, 2
	s_add_u32 s6, s0, s6
	v_and_b32_e32 v2, 31, v8
	v_lshlrev_b32_e32 v3, 2, v8
	s_movk_i32 s0, 0xff80
	v_and_or_b32 v0, v3, s0, v2
	s_addc_u32 s7, s7, 0
	v_ashrrev_i32_e32 v1, 31, v0
	v_lshl_add_u64 v[0:1], v[0:1], 2, s[6:7]
	s_barrier
	global_load_dword v176, v[0:1], off
	v_add_u32_e32 v9, 0x100, v8
	v_and_b32_e32 v83, 15, v8
	v_bfe_u32 v131, v8, 4, 2
	v_mov_b32_e32 v73, v169
	v_mov_b32_e32 v75, v169
	s_movk_i32 s3, 0x40c
	v_ashrrev_i32_e32 v130, 6, v8
	v_mov_b32_e32 v136, 0
	v_lshlrev_b32_e32 v132, 1, v130
	v_lshlrev_b32_e32 v133, 2, v131
	v_mov_b32_e32 v92, 0
	v_mov_b32_e32 v93, v136
	v_lshlrev_b32_e32 v0, 2, v9
	v_and_or_b32 v0, v0, s0, v2
	v_ashrrev_i32_e32 v1, 31, v0
	v_lshl_add_u64 v[0:1], v[0:1], 2, s[6:7]
	global_load_dword v177, v[0:1], off
	s_or_b32 s0, s11, s5
	s_or_b32 s0, s0, s9
	s_lshl_b64 s[6:7], s[0:1], 10
	s_add_u32 s6, s20, s6
	s_addc_u32 s7, s21, s7
	s_movk_i32 s5, 0x210
	v_or_b32_e32 v74, s0, v83
	s_lshl_b32 s11, s4, 4
	v_or_b32_e32 v72, 16, v74
	s_movk_i32 s0, 0x3020
	v_mov_b32_e32 v226, v3
	v_lshlrev_b32_e32 v0, 4, v8
	v_and_b32_e32 v168, 0x1f0, v0
	v_lshl_add_u64 v[0:1], s[6:7], 0, v[168:169]
	s_mov_b64 s[6:7], 0x15261200
	v_lshl_add_u64 v[4:5], v[0:1], 0, s[6:7]
	v_ashrrev_i32_e32 v0, 5, v8
	v_ashrrev_i32_e32 v1, 31, v0
	v_lshlrev_b64 v[2:3], 10, v[0:1]
	v_lshl_add_u64 v[2:3], v[4:5], 0, v[2:3]
	v_mad_u64_u32 v[6:7], s[6:7], v0, s5, v[168:169]
	global_load_dwordx4 v[180:183], v[2:3], off
	v_mov_b32_e32 v222, v6
	v_ashrrev_i32_e32 v0, 5, v9
	v_ashrrev_i32_e32 v1, 31, v0
	v_lshlrev_b64 v[2:3], 10, v[0:1]
	v_lshl_add_u64 v[2:3], v[4:5], 0, v[2:3]
	v_mad_u64_u32 v[6:7], s[6:7], v0, s5, v[168:169]
	global_load_dwordx4 v[184:187], v[2:3], off
	v_mov_b32_e32 v223, v6
	v_add_u32_e32 v0, 0x200, v8
	v_ashrrev_i32_e32 v0, 5, v0
	v_ashrrev_i32_e32 v1, 31, v0
	v_lshlrev_b64 v[2:3], 10, v[0:1]
	v_lshl_add_u64 v[2:3], v[4:5], 0, v[2:3]
	v_mad_u64_u32 v[6:7], s[6:7], v0, s5, v[168:169]
	global_load_dwordx4 v[188:191], v[2:3], off
	v_mov_b32_e32 v224, v6
	v_add_u32_e32 v0, 0x300, v8
	v_ashrrev_i32_e32 v0, 5, v0
	v_ashrrev_i32_e32 v1, 31, v0
	v_lshlrev_b64 v[2:3], 10, v[0:1]
	v_lshl_add_u64 v[2:3], v[4:5], 0, v[2:3]
	v_mad_u64_u32 v[4:5], s[6:7], v0, s5, v[168:169]
	global_load_dwordx4 v[192:195], v[2:3], off
	s_mov_b64 s[6:7], 0x7800b00
	v_mov_b32_e32 v225, v4
	s_waitcnt vmcnt(5)
	v_mul_f32_e32 v176, 0x3fb8aa3b, v176
	v_exp_f32_e32 v178, v176
	s_waitcnt vmcnt(4)
	v_mul_f32_e32 v177, 0x3fb8aa3b, v177
	v_exp_f32_e32 v179, v177
	ds_write2st64_b32 v226, v178, v179 offset0:196 offset1:200
	s_waitcnt vmcnt(3)
	ds_write_b128 v222, v[180:183]
	s_waitcnt vmcnt(2)
	ds_write_b128 v223, v[184:187]
	s_waitcnt vmcnt(1)
	ds_write_b128 v224, v[188:191]
	s_waitcnt vmcnt(0)
	ds_write_b128 v225, v[192:195]
	v_and_b32_e32 v0, 0x7fffff80, v8
	v_mul_u32_u24_e32 v1, 0x210, v83
	v_lshlrev_b32_e32 v2, 1, v0
	v_lshlrev_b32_e32 v3, 4, v131
	v_add3_u32 v134, v1, v2, v3
	v_mul_i32_i24_e32 v1, 0xfffffdf4, v83
	v_mad_u32_u24 v135, v83, s5, v1
	v_readlane_b32 s4, v253, 58
	v_lshlrev_b64 v[4:5], 11, v[72:73]
	v_readlane_b32 s5, v253, 59
	v_lshlrev_b32_e32 v0, 3, v131
	v_lshlrev_b32_e32 v2, 7, v83
	v_lshl_add_u64 v[76:77], s[4:5], 0, v[4:5]
	v_lshlrev_b64 v[4:5], 11, v[74:75]
	v_lshl_add_u64 v[84:85], s[4:5], 0, v[4:5]
	v_mov_b64_e32 v[4:5], s[20:21]
	v_mad_u64_u32 v[6:7], s[4:5], v74, s0, v[4:5]
	v_mad_u32_u24 v81, v83, s3, v135
	v_mad_u64_u32 v[4:5], s[4:5], v72, s0, v[4:5]
	v_or_b32_e32 v78, 32, v0
	v_or_b32_e32 v80, 64, v0
	v_or_b32_e32 v82, 0x60, v0
	v_lshl_add_u64 v[86:87], v[6:7], 0, s[6:7]
	s_movk_i32 s3, 0x3020
	v_lshl_add_u64 v[88:89], v[4:5], 0, s[6:7]
	v_add_u32_e32 v79, 0x4100, v81
	s_mov_b32 s0, 0
	s_mov_b64 s[4:5], -1
	v_lshlrev_b32_e32 v168, 1, v2
	v_lshlrev_b32_e32 v90, 1, v0
	s_waitcnt lgkmcnt(0)
	s_barrier
	s_branch .LBB0_43

.LBB0_101:
	s_and_b64 vcc, exec, s[4:5]
	s_cbranch_vccz .LBB0_39
	s_ashr_i32 s0, s8, 5
	s_bfe_u32 s6, s8, 0x30002
	s_lshl_b32 s4, s0, 10
	s_lshl_b32 s5, s6, 7
	s_or_b32 s7, s4, s5
	s_lshl_b32 s4, s0, 3
	s_or_b32 s4, s4, s6
	s_add_i32 s4, s4, 64
	s_ashr_i32 s5, s4, 31
	s_lshl_b64 s[4:5], s[4:5], 13
	v_readlane_b32 s10, v253, 56
	v_readlane_b32 s11, v253, 57
	s_add_u32 s4, s10, s4
	v_mov_b32_e32 v8, v171
	s_addc_u32 s5, s11, s5
	s_lshl_b32 s10, s9, 2
	s_add_u32 s4, s4, s10
	v_and_b32_e32 v2, 31, v8
	v_lshlrev_b32_e32 v3, 2, v8
	s_movk_i32 s10, 0xff80
	v_and_or_b32 v0, v3, s10, v2
	s_addc_u32 s5, s5, 0
	v_ashrrev_i32_e32 v1, 31, v0
	v_lshl_add_u64 v[0:1], v[0:1], 2, s[4:5]
	s_barrier
	global_load_dword v176, v[0:1], off
	v_add_u32_e32 v9, 0x100, v8
	v_and_b32_e32 v94, 15, v8
	v_bfe_u32 v96, v8, 4, 2
	v_ashrrev_i32_e32 v95, 6, v8
	s_movk_i32 s3, 0x40c
	v_mov_b32_e32 v101, 0
	v_lshlrev_b32_e32 v97, 1, v95
	v_lshlrev_b32_e32 v99, 2, v96
	v_mov_b32_e32 v36, 0
	v_mov_b32_e32 v37, v101
	v_lshlrev_b32_e32 v0, 2, v9
	v_and_or_b32 v0, v0, s10, v2
	v_ashrrev_i32_e32 v1, 31, v0
	v_lshl_add_u64 v[0:1], v[0:1], 2, s[4:5]
	global_load_dword v177, v[0:1], off
	s_or_b32 s4, s7, s9
	s_addk_i32 s4, 0x2000
	s_ashr_i32 s5, s4, 31
	s_lshl_b64 s[10:11], s[4:5], 10
	s_add_u32 s10, s20, s10
	s_addc_u32 s11, s21, s11
	s_movk_i32 s7, 0x210
	s_lshl_b32 s0, s0, 6
	s_lshl_b32 s5, s6, 3
	v_or_b32_e32 v34, s4, v94
	s_or_b32 s0, s5, s0
	v_or_b32_e32 v32, 16, v34
	v_readlane_b32 s4, v253, 58
	v_ashrrev_i32_e32 v35, 31, v34
	v_ashrrev_i32_e32 v33, 31, v32
	v_readlane_b32 s5, v253, 59
	s_movk_i32 s6, 0x3020
	v_mov_b32_e32 v226, v3
	v_lshlrev_b32_e32 v0, 4, v8
	v_and_b32_e32 v168, 0x1f0, v0
	v_lshl_add_u64 v[0:1], s[10:11], 0, v[168:169]
	s_mov_b64 s[10:11], 0x15261200
	v_lshl_add_u64 v[4:5], v[0:1], 0, s[10:11]
	v_ashrrev_i32_e32 v0, 5, v8
	v_ashrrev_i32_e32 v1, 31, v0
	v_lshlrev_b64 v[2:3], 10, v[0:1]
	v_lshl_add_u64 v[2:3], v[4:5], 0, v[2:3]
	v_mad_u64_u32 v[6:7], s[10:11], v0, s7, v[168:169]
	global_load_dwordx4 v[180:183], v[2:3], off
	v_mov_b32_e32 v222, v6
	v_ashrrev_i32_e32 v0, 5, v9
	v_ashrrev_i32_e32 v1, 31, v0
	v_lshlrev_b64 v[2:3], 10, v[0:1]
	v_lshl_add_u64 v[2:3], v[4:5], 0, v[2:3]
	v_mad_u64_u32 v[6:7], s[10:11], v0, s7, v[168:169]
	global_load_dwordx4 v[184:187], v[2:3], off
	v_mov_b32_e32 v223, v6
	v_add_u32_e32 v0, 0x200, v8
	v_ashrrev_i32_e32 v0, 5, v0
	v_ashrrev_i32_e32 v1, 31, v0
	v_lshlrev_b64 v[2:3], 10, v[0:1]
	v_lshl_add_u64 v[2:3], v[4:5], 0, v[2:3]
	v_mad_u64_u32 v[6:7], s[10:11], v0, s7, v[168:169]
	global_load_dwordx4 v[188:191], v[2:3], off
	v_mov_b32_e32 v224, v6
	v_add_u32_e32 v0, 0x300, v8
	v_ashrrev_i32_e32 v0, 5, v0
	v_ashrrev_i32_e32 v1, 31, v0
	v_lshlrev_b64 v[2:3], 10, v[0:1]
	v_lshl_add_u64 v[2:3], v[4:5], 0, v[2:3]
	v_mad_u64_u32 v[4:5], s[10:11], v0, s7, v[168:169]
	global_load_dwordx4 v[192:195], v[2:3], off
	s_mov_b64 s[10:11], 0x7800b00
	v_lshlrev_b32_e32 v168, 8, v94
	v_mov_b32_e32 v225, v4
	s_waitcnt vmcnt(5)
	v_mul_f32_e32 v176, 0x3fb8aa3b, v176
	v_exp_f32_e32 v178, v176
	s_waitcnt vmcnt(4)
	v_mul_f32_e32 v177, 0x3fb8aa3b, v177
	v_exp_f32_e32 v179, v177
	ds_write2st64_b32 v226, v178, v179 offset0:196 offset1:200
	s_waitcnt vmcnt(3)
	ds_write_b128 v222, v[180:183]
	s_waitcnt vmcnt(2)
	ds_write_b128 v223, v[184:187]
	s_waitcnt vmcnt(1)
	ds_write_b128 v224, v[188:191]
	s_waitcnt vmcnt(0)
	ds_write_b128 v225, v[192:195]
	v_and_b32_e32 v0, 0x7fffff80, v8
	v_mul_u32_u24_e32 v1, 0x210, v94
	v_lshlrev_b32_e32 v2, 1, v0
	v_lshlrev_b32_e32 v3, 4, v96
	v_lshlrev_b64 v[8:9], 11, v[34:35]
	v_add3_u32 v98, v1, v2, v3
	v_lshlrev_b64 v[2:3], 11, v[32:33]
	v_lshl_add_u64 v[40:41], s[4:5], 0, v[8:9]
	v_mov_b64_e32 v[8:9], s[20:21]
	v_mul_i32_i24_e32 v1, 0xfffffdf4, v94
	v_lshl_add_u64 v[38:39], s[4:5], 0, v[2:3]
	v_mad_i64_i32 v[10:11], s[4:5], v34, s6, v[8:9]
	v_mad_i64_i32 v[8:9], s[4:5], v32, s6, v[8:9]
	v_lshlrev_b32_e32 v0, 3, v96
	v_mad_u32_u24 v100, v94, s7, v1
	v_readlane_b32 s4, v253, 60
	v_or_b32_e32 v2, 32, v0
	v_or_b32_e32 v4, 64, v0
	v_or_b32_e32 v6, 0x60, v0
	v_mad_u32_u24 v93, v94, s3, v100
	v_readlane_b32 s5, v253, 61
	v_lshl_add_u64 v[42:43], v[10:11], 0, s[10:11]
	s_movk_i32 s3, 0x3020
	v_lshl_add_u64 v[44:45], v[8:9], 0, s[10:11]
	v_add_u32_e32 v92, 0x4100, v93
	v_lshl_add_u64 v[46:47], s[4:5], 0, v[168:169]
	s_mov_b32 s6, 0
	s_mov_b64 s[4:5], -1
	v_lshlrev_b32_e32 v168, 1, v0
	v_lshlrev_b32_e32 v48, 1, v2
	v_lshlrev_b32_e32 v50, 1, v4
	v_lshlrev_b32_e32 v52, 1, v6
	s_waitcnt lgkmcnt(0)
	s_barrier
